# adds EpiKV (MLA k_nope|v up-projection GEMMs, both instances): bf16 tile stores lane-permuted with ds_bpermute so 4 adjacent lanes write 64 contiguous bytes of one row (was 16 different rows per 16 la
# speedup vs baseline: 1.0122x; 1.0027x over previous
; __device__ __forceinline__ unsigned pk2(float lo, float hi) { f32x2 v = {lo, hi}; bf16x2_hw b = __builtin_convertvector(v, bf16x2_hw); return __builtin_bit_cast(unsigned, b); }
; __device__ __forceinline__ void st_bf8(bf16* p, f32x4 a, f32x4 b) { u32x4 w; w.x = pk2(a[0], a[1]); w.y = pk2(a[2], a[3]); w.z = pk2(b[0], b[1]); w.w = pk2(b[2], b[3]); *(u32x4*)p = w; }
;     __device__ __forceinline__ void operator()(AccRef acc, const pg8::Unit& u, int wr, int wc, int fr, int fq) const {
;         const int t = u.pn; bf16* O = t < 4 ? KN : VM; const int c0 = (t & 3) * 256;
;         EPI_LOOP_P( st_bf8(O + rw * 1024 + c0 + cl, v0, v1); )
.LBB0_712:
	v_mbcnt_lo_u32_b32 v148, -1, 0
	v_mbcnt_hi_u32_b32 v148, -1, v148
	v_lshrrev_b32_e32 v149, 2, v148
	v_and_b32_e32 v150, 3, v148
	v_and_b32_e32 v151, 0xfffffff0, v140
	v_or_b32_e32 v151, v151, v149
	v_and_b32_e32 v152, 0xffffffc0, v184
	v_lshl_or_b32 v152, v150, 4, v152
	v_mov_b32_e32 v153, 0
	v_lshlrev_b32_e32 v154, 6, v150
	v_lshl_or_b32 v154, v149, 2, v154
	s_cmp_lt_i32 s44, 4
	s_movk_i32 s18, 0x3000
	s_cselect_b32 s66, 0x2800, s18
	s_lshl_b64 s[18:19], s[66:67], s42
	s_add_u32 s18, s23, s18
	s_addc_u32 s19, s24, s19
	s_lshl_b32 s20, s44, 9
	v_lshl_add_u32 v144, s38, 8, v151
	s_and_b32 s20, s20, 0x600
	s_add_u32 s18, s18, s20
	v_ashrrev_i32_e32 v145, 31, v144
	v_cvt_pk_bf16_f32 v116, v116, v117
	v_cvt_pk_bf16_f32 v117, v118, v119
	v_cvt_pk_bf16_f32 v118, v112, v113
	v_or_b32_e32 v112, 16, v144
	s_addc_u32 s19, s19, 0
	v_lshlrev_b64 v[146:147], 11, v[144:145]
	v_ashrrev_i32_e32 v113, 31, v112
	v_cvt_pk_bf16_f32 v100, v100, v101
	v_cvt_pk_bf16_f32 v101, v102, v103
	v_cvt_pk_bf16_f32 v102, v96, v97
	v_or_b32_e32 v96, 32, v144
	v_lshl_add_u64 v[146:147], s[18:19], 0, v[146:147]
	v_lshlrev_b64 v[112:113], 11, v[112:113]
	v_ashrrev_i32_e32 v97, 31, v96
	v_cvt_pk_bf16_f32 v84, v84, v85
	v_cvt_pk_bf16_f32 v85, v86, v87
	v_cvt_pk_bf16_f32 v86, v80, v81
	v_or_b32_e32 v80, 48, v144
	v_lshl_add_u64 v[146:147], v[146:147], 0, v[152:153]
	v_cvt_pk_bf16_f32 v120, v120, v121
	v_cvt_pk_bf16_f32 v121, v122, v123
	v_cvt_pk_bf16_f32 v122, v124, v125
	v_cvt_pk_bf16_f32 v123, v126, v127
	v_cvt_pk_bf16_f32 v119, v114, v115
	v_lshl_add_u64 v[112:113], s[18:19], 0, v[112:113]
	v_lshlrev_b64 v[96:97], 11, v[96:97]
	v_ashrrev_i32_e32 v81, 31, v80
	v_cvt_pk_bf16_f32 v68, v68, v69
	v_cvt_pk_bf16_f32 v69, v70, v71
	v_cvt_pk_bf16_f32 v70, v64, v65
	v_add_u32_e32 v64, 0x80, v144
	ds_bpermute_b32 v156, v154, v120
	ds_bpermute_b32 v157, v154, v121
	ds_bpermute_b32 v158, v154, v122
	ds_bpermute_b32 v159, v154, v123
	ds_bpermute_b32 v160, v154, v116
	ds_bpermute_b32 v161, v154, v117
	ds_bpermute_b32 v162, v154, v118
	ds_bpermute_b32 v163, v154, v119
	s_waitcnt lgkmcnt(0)
	global_store_dwordx4 v[146:147], v[156:159], off
	global_store_dwordx4 v[146:147], v[160:163], off offset:256
	v_lshl_add_u64 v[112:113], v[112:113], 0, v[152:153]
	v_cvt_pk_bf16_f32 v108, v108, v109
	v_cvt_pk_bf16_f32 v109, v110, v111
	v_cvt_pk_bf16_f32 v110, v104, v105
	v_cvt_pk_bf16_f32 v111, v106, v107
	v_cvt_pk_bf16_f32 v103, v98, v99
	v_lshl_add_u64 v[96:97], s[18:19], 0, v[96:97]
	v_lshlrev_b64 v[80:81], 11, v[80:81]
	v_ashrrev_i32_e32 v65, 31, v64
	v_cvt_pk_bf16_f32 v52, v52, v53
	v_cvt_pk_bf16_f32 v53, v54, v55
	v_cvt_pk_bf16_f32 v54, v48, v49
	v_add_u32_e32 v48, 0x90, v144
	ds_bpermute_b32 v156, v154, v108
	ds_bpermute_b32 v157, v154, v109
	ds_bpermute_b32 v158, v154, v110
	ds_bpermute_b32 v159, v154, v111
	ds_bpermute_b32 v160, v154, v100
	ds_bpermute_b32 v161, v154, v101
	ds_bpermute_b32 v162, v154, v102
	ds_bpermute_b32 v163, v154, v103
	s_waitcnt lgkmcnt(0)
	global_store_dwordx4 v[112:113], v[156:159], off
	global_store_dwordx4 v[112:113], v[160:163], off offset:256
	v_lshl_add_u64 v[96:97], v[96:97], 0, v[152:153]
	v_cvt_pk_bf16_f32 v92, v92, v93
	v_cvt_pk_bf16_f32 v93, v94, v95
	v_cvt_pk_bf16_f32 v94, v88, v89
	v_cvt_pk_bf16_f32 v95, v90, v91
	v_cvt_pk_bf16_f32 v87, v82, v83
	v_lshl_add_u64 v[80:81], s[18:19], 0, v[80:81]
	v_lshlrev_b64 v[64:65], 11, v[64:65]
	v_ashrrev_i32_e32 v49, 31, v48
	v_cvt_pk_bf16_f32 v36, v36, v37
	v_cvt_pk_bf16_f32 v37, v38, v39
	v_cvt_pk_bf16_f32 v38, v32, v33
	v_add_u32_e32 v32, 0xa0, v144
	ds_bpermute_b32 v156, v154, v92
	ds_bpermute_b32 v157, v154, v93
	ds_bpermute_b32 v158, v154, v94
	ds_bpermute_b32 v159, v154, v95
	ds_bpermute_b32 v160, v154, v84
	ds_bpermute_b32 v161, v154, v85
	ds_bpermute_b32 v162, v154, v86
	ds_bpermute_b32 v163, v154, v87
	s_waitcnt lgkmcnt(0)
; __device__ __forceinline__ unsigned pk2(float lo, float hi) { f32x2 v = {lo, hi}; bf16x2_hw b = __builtin_convertvector(v, bf16x2_hw); return __builtin_bit_cast(unsigned, b); }
; __device__ __forceinline__ void st_bf8(bf16* p, f32x4 a, f32x4 b) { u32x4 w; w.x = pk2(a[0], a[1]); w.y = pk2(a[2], a[3]); w.z = pk2(b[0], b[1]); w.w = pk2(b[2], b[3]); *(u32x4*)p = w; }
;     __device__ __forceinline__ void operator()(AccRef acc, const pg8::Unit& u, int wr, int wc, int fr, int fq) const {
;         const int t = u.pn; bf16* O = t < 4 ? KN : VM; const int c0 = (t & 3) * 256;
;         EPI_LOOP_P( st_bf8(O + rw * 1024 + c0 + cl, v0, v1); )
	global_store_dwordx4 v[96:97], v[156:159], off
	global_store_dwordx4 v[96:97], v[160:163], off offset:256
	v_lshl_add_u64 v[80:81], v[80:81], 0, v[152:153]
	v_cvt_pk_bf16_f32 v76, v76, v77
	v_cvt_pk_bf16_f32 v77, v78, v79
	v_cvt_pk_bf16_f32 v78, v72, v73
	v_cvt_pk_bf16_f32 v79, v74, v75
	v_cvt_pk_bf16_f32 v71, v66, v67
	v_lshl_add_u64 v[64:65], s[18:19], 0, v[64:65]
	v_lshlrev_b64 v[48:49], 11, v[48:49]
	v_ashrrev_i32_e32 v33, 31, v32
	v_cvt_pk_bf16_f32 v20, v20, v21
	v_cvt_pk_bf16_f32 v21, v22, v23
	v_cvt_pk_bf16_f32 v22, v16, v17
	v_add_u32_e32 v16, 0xb0, v144
	ds_bpermute_b32 v156, v154, v76
	ds_bpermute_b32 v157, v154, v77
	ds_bpermute_b32 v158, v154, v78
	ds_bpermute_b32 v159, v154, v79
	ds_bpermute_b32 v160, v154, v68
	ds_bpermute_b32 v161, v154, v69
	ds_bpermute_b32 v162, v154, v70
	ds_bpermute_b32 v163, v154, v71
	s_waitcnt lgkmcnt(0)
	global_store_dwordx4 v[80:81], v[156:159], off
	global_store_dwordx4 v[80:81], v[160:163], off offset:256
	v_lshl_add_u64 v[64:65], v[64:65], 0, v[152:153]
	v_cvt_pk_bf16_f32 v60, v60, v61
	v_cvt_pk_bf16_f32 v61, v62, v63
	v_cvt_pk_bf16_f32 v62, v56, v57
	v_cvt_pk_bf16_f32 v63, v58, v59
	v_cvt_pk_bf16_f32 v55, v50, v51
	v_lshl_add_u64 v[48:49], s[18:19], 0, v[48:49]
	v_lshlrev_b64 v[32:33], 11, v[32:33]
	v_ashrrev_i32_e32 v17, 31, v16
	ds_bpermute_b32 v156, v154, v60
	ds_bpermute_b32 v157, v154, v61
	ds_bpermute_b32 v158, v154, v62
	ds_bpermute_b32 v159, v154, v63
	ds_bpermute_b32 v160, v154, v52
	ds_bpermute_b32 v161, v154, v53
	ds_bpermute_b32 v162, v154, v54
	ds_bpermute_b32 v163, v154, v55
	s_waitcnt lgkmcnt(0)
	global_store_dwordx4 v[64:65], v[156:159], off
	global_store_dwordx4 v[64:65], v[160:163], off offset:256
	v_lshl_add_u64 v[48:49], v[48:49], 0, v[152:153]
	v_cvt_pk_bf16_f32 v44, v44, v45
	v_cvt_pk_bf16_f32 v45, v46, v47
	v_cvt_pk_bf16_f32 v46, v40, v41
	v_cvt_pk_bf16_f32 v47, v42, v43
	v_cvt_pk_bf16_f32 v39, v34, v35
	v_lshl_add_u64 v[32:33], s[18:19], 0, v[32:33]
	v_lshlrev_b64 v[16:17], 11, v[16:17]
	ds_bpermute_b32 v156, v154, v44
	ds_bpermute_b32 v157, v154, v45
	ds_bpermute_b32 v158, v154, v46
	ds_bpermute_b32 v159, v154, v47
	ds_bpermute_b32 v160, v154, v36
	ds_bpermute_b32 v161, v154, v37
	ds_bpermute_b32 v162, v154, v38
	ds_bpermute_b32 v163, v154, v39
	s_waitcnt lgkmcnt(0)
	global_store_dwordx4 v[48:49], v[156:159], off
	global_store_dwordx4 v[48:49], v[160:163], off offset:256
	v_lshl_add_u64 v[32:33], v[32:33], 0, v[152:153]
	v_cvt_pk_bf16_f32 v28, v28, v29
	v_cvt_pk_bf16_f32 v29, v30, v31
	v_cvt_pk_bf16_f32 v30, v24, v25
	v_cvt_pk_bf16_f32 v31, v26, v27
	v_cvt_pk_bf16_f32 v23, v18, v19
	v_lshl_add_u64 v[16:17], s[18:19], 0, v[16:17]
	ds_bpermute_b32 v156, v154, v28
	ds_bpermute_b32 v157, v154, v29
	ds_bpermute_b32 v158, v154, v30
	ds_bpermute_b32 v159, v154, v31
	ds_bpermute_b32 v160, v154, v20
	ds_bpermute_b32 v161, v154, v21
	ds_bpermute_b32 v162, v154, v22
	ds_bpermute_b32 v163, v154, v23
	s_waitcnt lgkmcnt(0)
	global_store_dwordx4 v[32:33], v[156:159], off
	global_store_dwordx4 v[32:33], v[160:163], off offset:256
	v_lshl_add_u64 v[16:17], v[16:17], 0, v[152:153]
	v_cvt_pk_bf16_f32 v12, v12, v13
	v_cvt_pk_bf16_f32 v13, v14, v15
	v_cvt_pk_bf16_f32 v14, v8, v9
	v_cvt_pk_bf16_f32 v15, v10, v11
	v_cvt_pk_bf16_f32 v4, v4, v5
	v_cvt_pk_bf16_f32 v5, v6, v7
	v_cvt_pk_bf16_f32 v6, v0, v1
	v_cvt_pk_bf16_f32 v7, v2, v3
	ds_bpermute_b32 v156, v154, v12
	ds_bpermute_b32 v157, v154, v13
	ds_bpermute_b32 v158, v154, v14
	ds_bpermute_b32 v159, v154, v15
	ds_bpermute_b32 v160, v154, v4
	ds_bpermute_b32 v161, v154, v5
	ds_bpermute_b32 v162, v154, v6
	ds_bpermute_b32 v163, v154, v7
	s_waitcnt lgkmcnt(0)
	global_store_dwordx4 v[16:17], v[156:159], off
	global_store_dwordx4 v[16:17], v[160:163], off offset:256
	s_and_b64 vcc, exec, s[0:1]
	s_mov_b64 s[0:1], -1
	s_cbranch_vccnz .LBB0_699
	s_andn2_b64 vcc, exec, s[10:11]
	s_cbranch_vccnz .LBB0_698
	s_barrier
	s_branch .LBB0_698

; __device__ __forceinline__ unsigned pk2(float lo, float hi) { f32x2 v = {lo, hi}; bf16x2_hw b = __builtin_convertvector(v, bf16x2_hw); return __builtin_bit_cast(unsigned, b); }
; __device__ __forceinline__ void st_bf8(bf16* p, f32x4 a, f32x4 b) { u32x4 w; w.x = pk2(a[0], a[1]); w.y = pk2(a[2], a[3]); w.z = pk2(b[0], b[1]); w.w = pk2(b[2], b[3]); *(u32x4*)p = w; }
;     __device__ __forceinline__ void operator()(AccRef acc, const pg8::Unit& u, int wr, int wc, int fr, int fq) const {
;         const int t = u.pn; bf16* O = t < 4 ? KN : VM; const int c0 = (t & 3) * 256;
;         EPI_LOOP_P( st_bf8(O + rw * 1024 + c0 + cl, v0, v1); )
.LBB0_735:
	v_mbcnt_lo_u32_b32 v148, -1, 0
	v_mbcnt_hi_u32_b32 v148, -1, v148
	v_lshrrev_b32_e32 v149, 2, v148
	v_and_b32_e32 v150, 3, v148
	v_and_b32_e32 v151, 0xfffffff0, v140
	v_or_b32_e32 v151, v151, v149
	v_and_b32_e32 v152, 0xffffffc0, v184
	v_lshl_or_b32 v152, v150, 4, v152
	v_mov_b32_e32 v153, 0
	v_lshlrev_b32_e32 v154, 6, v150
	v_lshl_or_b32 v154, v149, 2, v154
	s_cmp_lt_i32 s40, 4
	s_mov_b32 s16, 0x35e00000
	s_cselect_b32 s16, s16, 0x39e00000
	s_add_u32 s16, s21, s16
	s_addc_u32 s17, s20, 0
	s_lshl_b32 s18, s40, 9
	v_lshl_add_u32 v144, s41, 8, v151
	s_and_b32 s18, s18, 0x600
	s_add_u32 s16, s16, s18
	v_ashrrev_i32_e32 v145, 31, v144
	v_cvt_pk_bf16_f32 v116, v116, v117
	v_cvt_pk_bf16_f32 v117, v118, v119
	v_cvt_pk_bf16_f32 v118, v112, v113
	v_or_b32_e32 v112, 16, v144
	s_addc_u32 s17, s17, 0
	v_lshlrev_b64 v[146:147], 11, v[144:145]
	v_ashrrev_i32_e32 v113, 31, v112
	v_cvt_pk_bf16_f32 v100, v100, v101
	v_cvt_pk_bf16_f32 v101, v102, v103
	v_cvt_pk_bf16_f32 v102, v96, v97
	v_or_b32_e32 v96, 32, v144
	v_lshl_add_u64 v[146:147], s[16:17], 0, v[146:147]
	v_lshlrev_b64 v[112:113], 11, v[112:113]
	v_ashrrev_i32_e32 v97, 31, v96
	v_cvt_pk_bf16_f32 v84, v84, v85
	v_cvt_pk_bf16_f32 v85, v86, v87
	v_cvt_pk_bf16_f32 v86, v80, v81
	v_or_b32_e32 v80, 48, v144
	v_lshl_add_u64 v[146:147], v[146:147], 0, v[152:153]
	v_cvt_pk_bf16_f32 v120, v120, v121
	v_cvt_pk_bf16_f32 v121, v122, v123
	v_cvt_pk_bf16_f32 v122, v124, v125
	v_cvt_pk_bf16_f32 v123, v126, v127
	v_cvt_pk_bf16_f32 v119, v114, v115
	v_lshl_add_u64 v[112:113], s[16:17], 0, v[112:113]
	v_lshlrev_b64 v[96:97], 11, v[96:97]
	v_ashrrev_i32_e32 v81, 31, v80
	v_cvt_pk_bf16_f32 v68, v68, v69
	v_cvt_pk_bf16_f32 v69, v70, v71
	v_cvt_pk_bf16_f32 v70, v64, v65
	v_add_u32_e32 v64, 0x80, v144
	ds_bpermute_b32 v156, v154, v120
	ds_bpermute_b32 v157, v154, v121
	ds_bpermute_b32 v158, v154, v122
	ds_bpermute_b32 v159, v154, v123
	ds_bpermute_b32 v160, v154, v116
	ds_bpermute_b32 v161, v154, v117
	ds_bpermute_b32 v162, v154, v118
	ds_bpermute_b32 v163, v154, v119
	s_waitcnt lgkmcnt(0)
	global_store_dwordx4 v[146:147], v[156:159], off
	global_store_dwordx4 v[146:147], v[160:163], off offset:256
	v_lshl_add_u64 v[112:113], v[112:113], 0, v[152:153]
	v_cvt_pk_bf16_f32 v108, v108, v109
	v_cvt_pk_bf16_f32 v109, v110, v111
	v_cvt_pk_bf16_f32 v110, v104, v105
	v_cvt_pk_bf16_f32 v111, v106, v107
	v_cvt_pk_bf16_f32 v103, v98, v99
	v_lshl_add_u64 v[96:97], s[16:17], 0, v[96:97]
	v_lshlrev_b64 v[80:81], 11, v[80:81]
	v_ashrrev_i32_e32 v65, 31, v64
	v_cvt_pk_bf16_f32 v52, v52, v53
	v_cvt_pk_bf16_f32 v53, v54, v55
	v_cvt_pk_bf16_f32 v54, v48, v49
	v_add_u32_e32 v48, 0x90, v144
	ds_bpermute_b32 v156, v154, v108
	ds_bpermute_b32 v157, v154, v109
	ds_bpermute_b32 v158, v154, v110
	ds_bpermute_b32 v159, v154, v111
	ds_bpermute_b32 v160, v154, v100
	ds_bpermute_b32 v161, v154, v101
	ds_bpermute_b32 v162, v154, v102
	ds_bpermute_b32 v163, v154, v103
	s_waitcnt lgkmcnt(0)
	global_store_dwordx4 v[112:113], v[156:159], off
	global_store_dwordx4 v[112:113], v[160:163], off offset:256
	v_lshl_add_u64 v[96:97], v[96:97], 0, v[152:153]
	v_cvt_pk_bf16_f32 v92, v92, v93
	v_cvt_pk_bf16_f32 v93, v94, v95
	v_cvt_pk_bf16_f32 v94, v88, v89
	v_cvt_pk_bf16_f32 v95, v90, v91
	v_cvt_pk_bf16_f32 v87, v82, v83
	v_lshl_add_u64 v[80:81], s[16:17], 0, v[80:81]
	v_lshlrev_b64 v[64:65], 11, v[64:65]
	v_ashrrev_i32_e32 v49, 31, v48
	v_cvt_pk_bf16_f32 v36, v36, v37
	v_cvt_pk_bf16_f32 v37, v38, v39
	v_cvt_pk_bf16_f32 v38, v32, v33
	v_add_u32_e32 v32, 0xa0, v144
	ds_bpermute_b32 v156, v154, v92
	ds_bpermute_b32 v157, v154, v93
	ds_bpermute_b32 v158, v154, v94
	ds_bpermute_b32 v159, v154, v95
	ds_bpermute_b32 v160, v154, v84
	ds_bpermute_b32 v161, v154, v85
	ds_bpermute_b32 v162, v154, v86
	ds_bpermute_b32 v163, v154, v87
	s_waitcnt lgkmcnt(0)
; __device__ __forceinline__ unsigned pk2(float lo, float hi) { f32x2 v = {lo, hi}; bf16x2_hw b = __builtin_convertvector(v, bf16x2_hw); return __builtin_bit_cast(unsigned, b); }
; __device__ __forceinline__ void st_bf8(bf16* p, f32x4 a, f32x4 b) { u32x4 w; w.x = pk2(a[0], a[1]); w.y = pk2(a[2], a[3]); w.z = pk2(b[0], b[1]); w.w = pk2(b[2], b[3]); *(u32x4*)p = w; }
;     __device__ __forceinline__ void operator()(AccRef acc, const pg8::Unit& u, int wr, int wc, int fr, int fq) const {
;         const int t = u.pn; bf16* O = t < 4 ? KN : VM; const int c0 = (t & 3) * 256;
;         EPI_LOOP_P( st_bf8(O + rw * 1024 + c0 + cl, v0, v1); )
	global_store_dwordx4 v[96:97], v[156:159], off
	global_store_dwordx4 v[96:97], v[160:163], off offset:256
	v_lshl_add_u64 v[80:81], v[80:81], 0, v[152:153]
	v_cvt_pk_bf16_f32 v76, v76, v77
	v_cvt_pk_bf16_f32 v77, v78, v79
	v_cvt_pk_bf16_f32 v78, v72, v73
	v_cvt_pk_bf16_f32 v79, v74, v75
	v_cvt_pk_bf16_f32 v71, v66, v67
	v_lshl_add_u64 v[64:65], s[16:17], 0, v[64:65]
	v_lshlrev_b64 v[48:49], 11, v[48:49]
	v_ashrrev_i32_e32 v33, 31, v32
	v_cvt_pk_bf16_f32 v20, v20, v21
	v_cvt_pk_bf16_f32 v21, v22, v23
	v_cvt_pk_bf16_f32 v22, v16, v17
	v_add_u32_e32 v16, 0xb0, v144
	ds_bpermute_b32 v156, v154, v76
	ds_bpermute_b32 v157, v154, v77
	ds_bpermute_b32 v158, v154, v78
	ds_bpermute_b32 v159, v154, v79
	ds_bpermute_b32 v160, v154, v68
	ds_bpermute_b32 v161, v154, v69
	ds_bpermute_b32 v162, v154, v70
	ds_bpermute_b32 v163, v154, v71
	s_waitcnt lgkmcnt(0)
	global_store_dwordx4 v[80:81], v[156:159], off
	global_store_dwordx4 v[80:81], v[160:163], off offset:256
	v_lshl_add_u64 v[64:65], v[64:65], 0, v[152:153]
	v_cvt_pk_bf16_f32 v60, v60, v61
	v_cvt_pk_bf16_f32 v61, v62, v63
	v_cvt_pk_bf16_f32 v62, v56, v57
	v_cvt_pk_bf16_f32 v63, v58, v59
	v_cvt_pk_bf16_f32 v55, v50, v51
	v_lshl_add_u64 v[48:49], s[16:17], 0, v[48:49]
	v_lshlrev_b64 v[32:33], 11, v[32:33]
	v_ashrrev_i32_e32 v17, 31, v16
	ds_bpermute_b32 v156, v154, v60
	ds_bpermute_b32 v157, v154, v61
	ds_bpermute_b32 v158, v154, v62
	ds_bpermute_b32 v159, v154, v63
	ds_bpermute_b32 v160, v154, v52
	ds_bpermute_b32 v161, v154, v53
	ds_bpermute_b32 v162, v154, v54
	ds_bpermute_b32 v163, v154, v55
	s_waitcnt lgkmcnt(0)
	global_store_dwordx4 v[64:65], v[156:159], off
	global_store_dwordx4 v[64:65], v[160:163], off offset:256
	v_lshl_add_u64 v[48:49], v[48:49], 0, v[152:153]
	v_cvt_pk_bf16_f32 v44, v44, v45
	v_cvt_pk_bf16_f32 v45, v46, v47
	v_cvt_pk_bf16_f32 v46, v40, v41
	v_cvt_pk_bf16_f32 v47, v42, v43
	v_cvt_pk_bf16_f32 v39, v34, v35
	v_lshl_add_u64 v[32:33], s[16:17], 0, v[32:33]
	v_lshlrev_b64 v[16:17], 11, v[16:17]
	ds_bpermute_b32 v156, v154, v44
	ds_bpermute_b32 v157, v154, v45
	ds_bpermute_b32 v158, v154, v46
	ds_bpermute_b32 v159, v154, v47
	ds_bpermute_b32 v160, v154, v36
	ds_bpermute_b32 v161, v154, v37
	ds_bpermute_b32 v162, v154, v38
	ds_bpermute_b32 v163, v154, v39
	s_waitcnt lgkmcnt(0)
	global_store_dwordx4 v[48:49], v[156:159], off
	global_store_dwordx4 v[48:49], v[160:163], off offset:256
	v_lshl_add_u64 v[32:33], v[32:33], 0, v[152:153]
	v_cvt_pk_bf16_f32 v28, v28, v29
	v_cvt_pk_bf16_f32 v29, v30, v31
	v_cvt_pk_bf16_f32 v30, v24, v25
	v_cvt_pk_bf16_f32 v31, v26, v27
	v_cvt_pk_bf16_f32 v23, v18, v19
	v_lshl_add_u64 v[16:17], s[16:17], 0, v[16:17]
	ds_bpermute_b32 v156, v154, v28
	ds_bpermute_b32 v157, v154, v29
	ds_bpermute_b32 v158, v154, v30
	ds_bpermute_b32 v159, v154, v31
	ds_bpermute_b32 v160, v154, v20
	ds_bpermute_b32 v161, v154, v21
	ds_bpermute_b32 v162, v154, v22
	ds_bpermute_b32 v163, v154, v23
	s_waitcnt lgkmcnt(0)
	global_store_dwordx4 v[32:33], v[156:159], off
	global_store_dwordx4 v[32:33], v[160:163], off offset:256
	v_lshl_add_u64 v[16:17], v[16:17], 0, v[152:153]
	v_cvt_pk_bf16_f32 v12, v12, v13
	v_cvt_pk_bf16_f32 v13, v14, v15
	v_cvt_pk_bf16_f32 v14, v8, v9
	v_cvt_pk_bf16_f32 v15, v10, v11
	v_cvt_pk_bf16_f32 v4, v4, v5
	v_cvt_pk_bf16_f32 v5, v6, v7
	v_cvt_pk_bf16_f32 v6, v0, v1
	v_cvt_pk_bf16_f32 v7, v2, v3
	ds_bpermute_b32 v156, v154, v12
	ds_bpermute_b32 v157, v154, v13
	ds_bpermute_b32 v158, v154, v14
	ds_bpermute_b32 v159, v154, v15
	ds_bpermute_b32 v160, v154, v4
	ds_bpermute_b32 v161, v154, v5
	ds_bpermute_b32 v162, v154, v6
	ds_bpermute_b32 v163, v154, v7
	s_waitcnt lgkmcnt(0)
	global_store_dwordx4 v[16:17], v[156:159], off
	global_store_dwordx4 v[16:17], v[160:163], off offset:256
	s_and_b64 vcc, exec, s[0:1]
	s_mov_b64 s[0:1], -1
	s_cbranch_vccnz .LBB0_722
	s_andn2_b64 vcc, exec, s[8:9]
	s_cbranch_vccnz .LBB0_721
	s_barrier
	s_branch .LBB0_721
